# loop-edge cleanup: removed 14 dead loop-carried v_mov copies in the attention tile loop
# speedup vs baseline: 1.0018x; 1.0018x over previous
; __device__ __forceinline__ void attn_items(const Ctx& C, const PV& P, int layer, int ctr_idx, unsigned char* smem) {
;     ...
;         for (int t = 0; t < T; ++t) {
;             if (t + 1 < T) gload((t + 1) * 64);
;             if (grp == 0) H1(t & 1); else if (t > 0) H2((t - 1) & 1);
;             __syncthreads();
;             if (t + 1 < T) lstore((t + 1) & 1);
;             if (grp == 0) H2(t & 1); else H1(t & 1);
;             __syncthreads();
;         }
.LBB0_571:
	s_or_b64 exec, exec, s[50:51]
	s_add_i32 s18, s18, 64
	v_cmp_eq_u32_e32 vcc, s4, v159
	s_or_b64 s[58:59], vcc, s[58:59]
	s_mov_b32 s5, s4
	s_waitcnt lgkmcnt(0)
	s_barrier
	s_andn2_b64 exec, exec, s[58:59]
	s_cbranch_execz .LBB0_593

; __device__ __forceinline__ unsigned pack2bf(float a, float b) { const f32x2 v = (f32x2){a, b}; const bf16x2_t h = __builtin_convertvector(v, bf16x2_t); return __builtin_bit_cast(unsigned, h); }
; __device__ __forceinline__ void attn_items(const Ctx& C, const PV& P, int layer, int ctr_idx, unsigned char* smem) {
;     ...
;                     for (int r = 0; r < 4; ++r) { pv[t][r] = __builtin_amdgcn_exp2f(st[t][qs][r] - mnew); ls += pv[t][r]; }
;                 l_run[qs] = l_run[qs] * alpha + ls;
;                 if (__builtin_amdgcn_ballot_w64(alpha != 1.0f) != 0ull) {
; #pragma unroll
;                     for (int a = 0; a < 8; ++a) O[a][qs] = O[a][qs] * alpha;
;                 }
; #pragma unroll
;                 for (int u = 0; u < 2; ++u) {
;                     union { bf16x8 v; unsigned w[4]; } pk;
;                     pk.w[0] = pack2bf(pv[2 * u][0], pv[2 * u][1]); pk.w[1] = pack2bf(pv[2 * u][2], pv[2 * u][3]);
;                     pk.w[2] = pack2bf(pv[2 * u + 1][0], pv[2 * u + 1][1]); pk.w[3] = pack2bf(pv[2 * u + 1][2], pv[2 * u + 1][3]);
;                     pb[qs][u] = pk.v;
;                 }
;             }
;         };
;         auto H2 = [&](int b) {
;             const unsigned char* sb = smem + b * 36864 + 18432;
;             __builtin_amdgcn_s_setprio(1);
; #pragma unroll
;             for (int u = 0; u < 2; ++u)
; #pragma unroll
;                 for (int a = 0; a < 8; ++a) {
;                     union { bf16x8 v; u32x2 h[2]; } vf;
;                     vf.h[0] = *(const u32x2*)(sb + (a * 16 + fr) * 144 + (u * 32 + fq * 4) * 2);
;                     vf.h[1] = *(const u32x2*)(sb + (a * 16 + fr) * 144 + (u * 32 + 16 + fq * 4) * 2);
;                     O[a][0] = __builtin_amdgcn_mfma_f32_16x16x32_bf16(vf.v, pb[0][u], O[a][0], 0, 0, 0);
;                     O[a][1] = __builtin_amdgcn_mfma_f32_16x16x32_bf16(vf.v, pb[1][u], O[a][1], 0, 0, 0);
;                 }
;             __builtin_amdgcn_s_setprio(0);
.LBB0_574:
	s_or_b64 exec, exec, s[60:61]
	s_and_saveexec_b64 s[6:7], s[42:43]
	s_xor_b64 s[60:61], exec, s[6:7]
	s_cbranch_execz .LBB0_577
	s_cmp_eq_u32 s5, 0
	s_cbranch_scc1 .LBB0_577
	s_andn2_b32 s6, 1, s5
	s_mul_i32 s6, s6, 0x9000
	v_add_u32_e32 v140, s6, v205
	ds_read_b64 v[232:233], v140 offset:18432
	ds_read_b64 v[234:235], v140 offset:18464
	ds_read_b64 v[236:237], v140 offset:20736
	ds_read_b64 v[238:239], v140 offset:20768
	ds_read_b64 v[240:241], v140 offset:23040
	ds_read_b64 v[242:243], v140 offset:23072
	s_waitcnt lgkmcnt(4)
	v_mfma_f32_16x16x32_bf16 v[108:111], v[232:235], v[0:3], v[108:111]
	v_mfma_f32_16x16x32_bf16 v[80:83], v[232:235], v[8:11], v[80:83]
	ds_read_b64 v[232:233], v140 offset:25344
	ds_read_b64 v[234:235], v140 offset:25376
	v_sub_f32_e32 v120, v120, v248
	v_sub_f32_e32 v112, v112, v249
	v_exp_f32_e32 v120, v120
	v_exp_f32_e32 v112, v112
	v_sub_f32_e32 v121, v121, v248
	v_sub_f32_e32 v113, v113, v249
	v_exp_f32_e32 v121, v121
	v_exp_f32_e32 v113, v113
	s_waitcnt lgkmcnt(4)
	v_mfma_f32_16x16x32_bf16 v[104:107], v[236:239], v[0:3], v[104:107]
	v_mfma_f32_16x16x32_bf16 v[68:71], v[236:239], v[8:11], v[68:71]
	ds_read_b64 v[236:237], v140 offset:27648
	ds_read_b64 v[238:239], v140 offset:27680
	v_sub_f32_e32 v122, v122, v248
	v_sub_f32_e32 v114, v114, v249
	v_exp_f32_e32 v122, v122
	v_exp_f32_e32 v114, v114
	v_sub_f32_e32 v123, v123, v248
	v_sub_f32_e32 v115, v115, v249
	v_exp_f32_e32 v123, v123
	v_exp_f32_e32 v115, v115
	s_waitcnt lgkmcnt(4)
	v_mfma_f32_16x16x32_bf16 v[100:103], v[240:243], v[0:3], v[100:103]
	v_mfma_f32_16x16x32_bf16 v[60:63], v[240:243], v[8:11], v[60:63]
	ds_read_b64 v[240:241], v140 offset:29952
	ds_read_b64 v[242:243], v140 offset:29984
	v_sub_f32_e32 v124, v124, v248
	v_sub_f32_e32 v116, v116, v249
	v_exp_f32_e32 v124, v124
	v_exp_f32_e32 v116, v116
	v_sub_f32_e32 v125, v125, v248
	v_sub_f32_e32 v117, v117, v249
	v_exp_f32_e32 v125, v125
	v_exp_f32_e32 v117, v117
	s_waitcnt lgkmcnt(4)
	v_mfma_f32_16x16x32_bf16 v[96:99], v[232:235], v[0:3], v[96:99]
	v_mfma_f32_16x16x32_bf16 v[52:55], v[232:235], v[8:11], v[52:55]
	ds_read_b64 v[232:233], v140 offset:32256
	ds_read_b64 v[234:235], v140 offset:32288
	v_sub_f32_e32 v126, v126, v248
	v_sub_f32_e32 v118, v118, v249
	v_exp_f32_e32 v126, v126
	v_exp_f32_e32 v118, v118
	v_sub_f32_e32 v127, v127, v248
	v_sub_f32_e32 v119, v119, v249
	v_exp_f32_e32 v127, v127
	v_exp_f32_e32 v119, v119
	s_waitcnt lgkmcnt(4)
	v_mfma_f32_16x16x32_bf16 v[92:95], v[236:239], v[0:3], v[92:95]
	v_mfma_f32_16x16x32_bf16 v[44:47], v[236:239], v[8:11], v[44:47]
	ds_read_b64 v[236:237], v140 offset:34560
	ds_read_b64 v[238:239], v140 offset:34592
	v_add_f32_e32 v245, v120, v245
	v_add_f32_e32 v247, v112, v247
	v_add_f32_e32 v245, v121, v245
	v_add_f32_e32 v247, v113, v247
	v_add_f32_e32 v245, v122, v245
	v_add_f32_e32 v247, v114, v247
	v_add_f32_e32 v245, v123, v245
	v_add_f32_e32 v247, v115, v247
	s_waitcnt lgkmcnt(4)
	v_mfma_f32_16x16x32_bf16 v[84:87], v[240:243], v[0:3], v[84:87]
	v_mfma_f32_16x16x32_bf16 v[40:43], v[240:243], v[8:11], v[40:43]
	ds_read_b64 v[240:241], v140 offset:18496
	ds_read_b64 v[242:243], v140 offset:18528
	v_add_f32_e32 v245, v124, v245
	v_add_f32_e32 v247, v116, v247
	v_add_f32_e32 v245, v125, v245
	v_add_f32_e32 v247, v117, v247
	v_add_f32_e32 v245, v126, v245
	v_add_f32_e32 v247, v118, v247
	v_add_f32_e32 v245, v127, v245
	v_add_f32_e32 v247, v119, v247
	s_waitcnt lgkmcnt(4)
	v_mfma_f32_16x16x32_bf16 v[76:79], v[232:235], v[0:3], v[76:79]
	v_mfma_f32_16x16x32_bf16 v[36:39], v[232:235], v[8:11], v[36:39]
	ds_read_b64 v[232:233], v140 offset:20800
	ds_read_b64 v[234:235], v140 offset:20832
	v_cvt_pk_bf16_f32 v4, v120, v121
	v_cvt_pk_bf16_f32 v12, v112, v113
	v_cvt_pk_bf16_f32 v5, v122, v123
	v_cvt_pk_bf16_f32 v13, v114, v115
	v_cvt_pk_bf16_f32 v6, v124, v125
	v_cvt_pk_bf16_f32 v14, v116, v117
	v_cvt_pk_bf16_f32 v7, v126, v127
	v_cvt_pk_bf16_f32 v15, v118, v119
	s_waitcnt lgkmcnt(4)
	v_mfma_f32_16x16x32_bf16 v[64:67], v[236:239], v[0:3], v[64:67]
	v_mfma_f32_16x16x32_bf16 v[32:35], v[236:239], v[8:11], v[32:35]
	ds_read_b64 v[236:237], v140 offset:23104
	ds_read_b64 v[238:239], v140 offset:23136
	v_fma_f32 v250, v250, v244, v245
	v_fma_f32 v251, v251, v246, v247
	v_mov_b32_e32 v161, v250
	v_mov_b32_e32 v157, v251
	s_waitcnt lgkmcnt(4)
	v_mfma_f32_16x16x32_bf16 v[108:111], v[240:243], v[4:7], v[108:111]
	v_mfma_f32_16x16x32_bf16 v[80:83], v[240:243], v[12:15], v[80:83]
	ds_read_b64 v[240:241], v140 offset:25408
	ds_read_b64 v[242:243], v140 offset:25440
	s_waitcnt lgkmcnt(4)
	v_mfma_f32_16x16x32_bf16 v[104:107], v[232:235], v[4:7], v[104:107]
	v_mfma_f32_16x16x32_bf16 v[68:71], v[232:235], v[12:15], v[68:71]
	ds_read_b64 v[232:233], v140 offset:27712
	ds_read_b64 v[234:235], v140 offset:27744
	s_waitcnt lgkmcnt(4)
	v_mfma_f32_16x16x32_bf16 v[100:103], v[236:239], v[4:7], v[100:103]
	v_mfma_f32_16x16x32_bf16 v[60:63], v[236:239], v[12:15], v[60:63]
	ds_read_b64 v[236:237], v140 offset:30016
	ds_read_b64 v[238:239], v140 offset:30048
	s_waitcnt lgkmcnt(4)
	v_mfma_f32_16x16x32_bf16 v[96:99], v[240:243], v[4:7], v[96:99]
	v_mfma_f32_16x16x32_bf16 v[52:55], v[240:243], v[12:15], v[52:55]
	ds_read_b64 v[240:241], v140 offset:32320
	ds_read_b64 v[242:243], v140 offset:32352
	s_waitcnt lgkmcnt(4)
	v_mfma_f32_16x16x32_bf16 v[92:95], v[232:235], v[4:7], v[92:95]
	v_mfma_f32_16x16x32_bf16 v[44:47], v[232:235], v[12:15], v[44:47]
	ds_read_b64 v[232:233], v140 offset:34624
	ds_read_b64 v[234:235], v140 offset:34656
	s_waitcnt lgkmcnt(4)
	v_mfma_f32_16x16x32_bf16 v[84:87], v[236:239], v[4:7], v[84:87]
	v_mfma_f32_16x16x32_bf16 v[40:43], v[236:239], v[12:15], v[40:43]
	s_waitcnt lgkmcnt(2)
	v_mfma_f32_16x16x32_bf16 v[76:79], v[240:243], v[4:7], v[76:79]
	v_mfma_f32_16x16x32_bf16 v[36:39], v[240:243], v[12:15], v[36:39]
	s_waitcnt lgkmcnt(0)
	v_mfma_f32_16x16x32_bf16 v[64:67], v[232:235], v[4:7], v[64:67]
	v_mfma_f32_16x16x32_bf16 v[32:35], v[232:235], v[12:15], v[32:35]

; __device__ __forceinline__ void attn_items(const Ctx& C, const PV& P, int layer, int ctr_idx, unsigned char* smem) {
;     ...
;         auto lstore = [&](int b) {
;             unsigned char* sb = smem + b * 36864;
; #pragma unroll
;             for (int i = 0; i < 2; ++i) {
;                 const int row = lrow + 64 * i;
;                 *(u32x4*)(sb + row * 144 + lkc * 2) = rk[i];
;                 *(u32x4*)(sb + 18432 + row * 144 + lkc * 2) = rv[i];
;             }
;         };
;     ...
;             __syncthreads();
;             if (t + 1 < T) lstore((t + 1) & 1);
.LBB0_583:
	s_or_b64 exec, exec, s[60:61]
	s_barrier
	s_and_saveexec_b64 s[60:61], s[50:51]
	s_cbranch_execz .LBB0_585
	s_bitcmp1_b32 s4, 0
	s_cselect_b32 s6, 0x9000, 0
	v_add_u32_e32 v140, s6, v204
	s_waitcnt vmcnt(3)
	ds_write_b128 v140, v[48:51]
	s_waitcnt vmcnt(2)
	ds_write_b128 v140, v[56:59] offset:18432
	s_waitcnt vmcnt(1)
	ds_write_b128 v140, v[72:75] offset:9216
	s_waitcnt vmcnt(0)
	ds_write_b128 v140, v[88:91] offset:27648

; __device__ __forceinline__ unsigned pack2bf(float a, float b) { const f32x2 v = (f32x2){a, b}; const bf16x2_t h = __builtin_convertvector(v, bf16x2_t); return __builtin_bit_cast(unsigned, h); }
; __device__ __forceinline__ void attn_items(const Ctx& C, const PV& P, int layer, int ctr_idx, unsigned char* smem) {
;     ...
;                     for (int r = 0; r < 4; ++r) { pv[t][r] = __builtin_amdgcn_exp2f(st[t][qs][r] - mnew); ls += pv[t][r]; }
;                 l_run[qs] = l_run[qs] * alpha + ls;
;                 if (__builtin_amdgcn_ballot_w64(alpha != 1.0f) != 0ull) {
; #pragma unroll
;                     for (int a = 0; a < 8; ++a) O[a][qs] = O[a][qs] * alpha;
;                 }
; #pragma unroll
;                 for (int u = 0; u < 2; ++u) {
;                     union { bf16x8 v; unsigned w[4]; } pk;
;                     pk.w[0] = pack2bf(pv[2 * u][0], pv[2 * u][1]); pk.w[1] = pack2bf(pv[2 * u][2], pv[2 * u][3]);
;                     pk.w[2] = pack2bf(pv[2 * u + 1][0], pv[2 * u + 1][1]); pk.w[3] = pack2bf(pv[2 * u + 1][2], pv[2 * u + 1][3]);
;                     pb[qs][u] = pk.v;
;                 }
;             }
;         };
;         auto H2 = [&](int b) {
;             const unsigned char* sb = smem + b * 36864 + 18432;
;             __builtin_amdgcn_s_setprio(1);
; #pragma unroll
;             for (int u = 0; u < 2; ++u)
; #pragma unroll
;                 for (int a = 0; a < 8; ++a) {
;                     union { bf16x8 v; u32x2 h[2]; } vf;
;                     vf.h[0] = *(const u32x2*)(sb + (a * 16 + fr) * 144 + (u * 32 + fq * 4) * 2);
;                     vf.h[1] = *(const u32x2*)(sb + (a * 16 + fr) * 144 + (u * 32 + 16 + fq * 4) * 2);
;                     O[a][0] = __builtin_amdgcn_mfma_f32_16x16x32_bf16(vf.v, pb[0][u], O[a][0], 0, 0, 0);
;                     O[a][1] = __builtin_amdgcn_mfma_f32_16x16x32_bf16(vf.v, pb[1][u], O[a][1], 0, 0, 0);
;                 }
;             __builtin_amdgcn_s_setprio(0);
;         };
.LBB0_591:
	s_andn2_saveexec_b64 s[50:51], s[50:51]
	s_cbranch_execz .LBB0_571
	v_add_u32_e32 v140, s5, v205
	ds_read_b64 v[232:233], v140 offset:18432
	ds_read_b64 v[234:235], v140 offset:18464
	ds_read_b64 v[236:237], v140 offset:20736
	ds_read_b64 v[238:239], v140 offset:20768
	ds_read_b64 v[240:241], v140 offset:23040
	ds_read_b64 v[242:243], v140 offset:23072
	s_waitcnt lgkmcnt(4)
	v_mfma_f32_16x16x32_bf16 v[108:111], v[232:235], v[0:3], v[108:111]
	v_mfma_f32_16x16x32_bf16 v[80:83], v[232:235], v[8:11], v[80:83]
	ds_read_b64 v[232:233], v140 offset:25344
	ds_read_b64 v[234:235], v140 offset:25376
	v_sub_f32_e32 v120, v120, v248
	v_sub_f32_e32 v112, v112, v249
	v_exp_f32_e32 v120, v120
	v_exp_f32_e32 v112, v112
	v_sub_f32_e32 v121, v121, v248
	v_sub_f32_e32 v113, v113, v249
	v_exp_f32_e32 v121, v121
	v_exp_f32_e32 v113, v113
	s_waitcnt lgkmcnt(4)
	v_mfma_f32_16x16x32_bf16 v[104:107], v[236:239], v[0:3], v[104:107]
	v_mfma_f32_16x16x32_bf16 v[68:71], v[236:239], v[8:11], v[68:71]
	ds_read_b64 v[236:237], v140 offset:27648
	ds_read_b64 v[238:239], v140 offset:27680
	v_sub_f32_e32 v122, v122, v248
	v_sub_f32_e32 v114, v114, v249
	v_exp_f32_e32 v122, v122
	v_exp_f32_e32 v114, v114
	v_sub_f32_e32 v123, v123, v248
	v_sub_f32_e32 v115, v115, v249
	v_exp_f32_e32 v123, v123
	v_exp_f32_e32 v115, v115
	s_waitcnt lgkmcnt(4)
	v_mfma_f32_16x16x32_bf16 v[100:103], v[240:243], v[0:3], v[100:103]
	v_mfma_f32_16x16x32_bf16 v[60:63], v[240:243], v[8:11], v[60:63]
	ds_read_b64 v[240:241], v140 offset:29952
	ds_read_b64 v[242:243], v140 offset:29984
	v_sub_f32_e32 v124, v124, v248
	v_sub_f32_e32 v116, v116, v249
	v_exp_f32_e32 v124, v124
	v_exp_f32_e32 v116, v116
	v_sub_f32_e32 v125, v125, v248
	v_sub_f32_e32 v117, v117, v249
	v_exp_f32_e32 v125, v125
	v_exp_f32_e32 v117, v117
	s_waitcnt lgkmcnt(4)
	v_mfma_f32_16x16x32_bf16 v[96:99], v[232:235], v[0:3], v[96:99]
	v_mfma_f32_16x16x32_bf16 v[52:55], v[232:235], v[8:11], v[52:55]
	ds_read_b64 v[232:233], v140 offset:32256
	ds_read_b64 v[234:235], v140 offset:32288
	v_sub_f32_e32 v126, v126, v248
	v_sub_f32_e32 v118, v118, v249
	v_exp_f32_e32 v126, v126
	v_exp_f32_e32 v118, v118
	v_sub_f32_e32 v127, v127, v248
	v_sub_f32_e32 v119, v119, v249
	v_exp_f32_e32 v127, v127
	v_exp_f32_e32 v119, v119
	s_waitcnt lgkmcnt(4)
	v_mfma_f32_16x16x32_bf16 v[92:95], v[236:239], v[0:3], v[92:95]
	v_mfma_f32_16x16x32_bf16 v[44:47], v[236:239], v[8:11], v[44:47]
	ds_read_b64 v[236:237], v140 offset:34560
	ds_read_b64 v[238:239], v140 offset:34592
	v_add_f32_e32 v245, v120, v245
	v_add_f32_e32 v247, v112, v247
	v_add_f32_e32 v245, v121, v245
	v_add_f32_e32 v247, v113, v247
	v_add_f32_e32 v245, v122, v245
	v_add_f32_e32 v247, v114, v247
	v_add_f32_e32 v245, v123, v245
	v_add_f32_e32 v247, v115, v247
	s_waitcnt lgkmcnt(4)
	v_mfma_f32_16x16x32_bf16 v[84:87], v[240:243], v[0:3], v[84:87]
	v_mfma_f32_16x16x32_bf16 v[40:43], v[240:243], v[8:11], v[40:43]
	ds_read_b64 v[240:241], v140 offset:18496
	ds_read_b64 v[242:243], v140 offset:18528
	v_add_f32_e32 v245, v124, v245
	v_add_f32_e32 v247, v116, v247
	v_add_f32_e32 v245, v125, v245
	v_add_f32_e32 v247, v117, v247
	v_add_f32_e32 v245, v126, v245
	v_add_f32_e32 v247, v118, v247
	v_add_f32_e32 v245, v127, v245
	v_add_f32_e32 v247, v119, v247
	s_waitcnt lgkmcnt(4)
	v_mfma_f32_16x16x32_bf16 v[76:79], v[232:235], v[0:3], v[76:79]
	v_mfma_f32_16x16x32_bf16 v[36:39], v[232:235], v[8:11], v[36:39]
	ds_read_b64 v[232:233], v140 offset:20800
	ds_read_b64 v[234:235], v140 offset:20832
	v_cvt_pk_bf16_f32 v4, v120, v121
	v_cvt_pk_bf16_f32 v12, v112, v113
	v_cvt_pk_bf16_f32 v5, v122, v123
	v_cvt_pk_bf16_f32 v13, v114, v115
	v_cvt_pk_bf16_f32 v6, v124, v125
	v_cvt_pk_bf16_f32 v14, v116, v117
	v_cvt_pk_bf16_f32 v7, v126, v127
	v_cvt_pk_bf16_f32 v15, v118, v119
	s_waitcnt lgkmcnt(4)
	v_mfma_f32_16x16x32_bf16 v[64:67], v[236:239], v[0:3], v[64:67]
	v_mfma_f32_16x16x32_bf16 v[32:35], v[236:239], v[8:11], v[32:35]
	ds_read_b64 v[236:237], v140 offset:23104
	ds_read_b64 v[238:239], v140 offset:23136
	v_fma_f32 v250, v250, v244, v245
	v_fma_f32 v251, v251, v246, v247
	v_mov_b32_e32 v161, v250
	v_mov_b32_e32 v157, v251
	s_waitcnt lgkmcnt(4)
	v_mfma_f32_16x16x32_bf16 v[108:111], v[240:243], v[4:7], v[108:111]
	v_mfma_f32_16x16x32_bf16 v[80:83], v[240:243], v[12:15], v[80:83]
	ds_read_b64 v[240:241], v140 offset:25408
	ds_read_b64 v[242:243], v140 offset:25440
	s_waitcnt lgkmcnt(4)
	v_mfma_f32_16x16x32_bf16 v[104:107], v[232:235], v[4:7], v[104:107]
	v_mfma_f32_16x16x32_bf16 v[68:71], v[232:235], v[12:15], v[68:71]
	ds_read_b64 v[232:233], v140 offset:27712
	ds_read_b64 v[234:235], v140 offset:27744
	s_waitcnt lgkmcnt(4)
	v_mfma_f32_16x16x32_bf16 v[100:103], v[236:239], v[4:7], v[100:103]
	v_mfma_f32_16x16x32_bf16 v[60:63], v[236:239], v[12:15], v[60:63]
	ds_read_b64 v[236:237], v140 offset:30016
	ds_read_b64 v[238:239], v140 offset:30048
	s_waitcnt lgkmcnt(4)
	v_mfma_f32_16x16x32_bf16 v[96:99], v[240:243], v[4:7], v[96:99]
	v_mfma_f32_16x16x32_bf16 v[52:55], v[240:243], v[12:15], v[52:55]
	ds_read_b64 v[240:241], v140 offset:32320
	ds_read_b64 v[242:243], v140 offset:32352
	s_waitcnt lgkmcnt(4)
	v_mfma_f32_16x16x32_bf16 v[92:95], v[232:235], v[4:7], v[92:95]
	v_mfma_f32_16x16x32_bf16 v[44:47], v[232:235], v[12:15], v[44:47]
	ds_read_b64 v[232:233], v140 offset:34624
	ds_read_b64 v[234:235], v140 offset:34656
	s_waitcnt lgkmcnt(4)
	v_mfma_f32_16x16x32_bf16 v[84:87], v[236:239], v[4:7], v[84:87]
	v_mfma_f32_16x16x32_bf16 v[40:43], v[236:239], v[12:15], v[40:43]
	s_waitcnt lgkmcnt(2)
	v_mfma_f32_16x16x32_bf16 v[76:79], v[240:243], v[4:7], v[76:79]
	v_mfma_f32_16x16x32_bf16 v[36:39], v[240:243], v[12:15], v[36:39]
	s_waitcnt lgkmcnt(0)
	v_mfma_f32_16x16x32_bf16 v[64:67], v[232:235], v[4:7], v[64:67]
	v_mfma_f32_16x16x32_bf16 v[32:35], v[232:235], v[12:15], v[32:35]
	s_branch .LBB0_571
; __device__ __forceinline__ unsigned pack2bf(float a, float b) { const f32x2 v = (f32x2){a, b}; const bf16x2_t h = __builtin_convertvector(v, bf16x2_t); return __builtin_bit_cast(unsigned, h); }
; __device__ __forceinline__ void attn_items(const Ctx& C, const PV& P, int layer, int ctr_idx, unsigned char* smem) {
;     ...
;                     for (int r = 0; r < 4; ++r) { pv[t][r] = __builtin_amdgcn_exp2f(st[t][qs][r] - mnew); ls += pv[t][r]; }
;                 l_run[qs] = l_run[qs] * alpha + ls;
;                 if (__builtin_amdgcn_ballot_w64(alpha != 1.0f) != 0ull) {
; #pragma unroll
;                     for (int a = 0; a < 8; ++a) O[a][qs] = O[a][qs] * alpha;
;                 }
; #pragma unroll
;                 for (int u = 0; u < 2; ++u) {
;                     union { bf16x8 v; unsigned w[4]; } pk;
;                     pk.w[0] = pack2bf(pv[2 * u][0], pv[2 * u][1]); pk.w[1] = pack2bf(pv[2 * u][2], pv[2 * u][3]);
;                     pk.w[2] = pack2bf(pv[2 * u + 1][0], pv[2 * u + 1][1]); pk.w[3] = pack2bf(pv[2 * u + 1][2], pv[2 * u + 1][3]);
;                     pb[qs][u] = pk.v;
;                 }
;             }
;         };
;         auto H2 = [&](int b) {
;             const unsigned char* sb = smem + b * 36864 + 18432;
;             __builtin_amdgcn_s_setprio(1);
; #pragma unroll
;             for (int u = 0; u < 2; ++u)
; #pragma unroll
;                 for (int a = 0; a < 8; ++a) {
;                     union { bf16x8 v; u32x2 h[2]; } vf;
;                     vf.h[0] = *(const u32x2*)(sb + (a * 16 + fr) * 144 + (u * 32 + fq * 4) * 2);
;                     vf.h[1] = *(const u32x2*)(sb + (a * 16 + fr) * 144 + (u * 32 + 16 + fq * 4) * 2);
;                     O[a][0] = __builtin_amdgcn_mfma_f32_16x16x32_bf16(vf.v, pb[0][u], O[a][0], 0, 0, 0);
;                     O[a][1] = __builtin_amdgcn_mfma_f32_16x16x32_bf16(vf.v, pb[1][u], O[a][1], 0, 0, 0);
;                 }
;             __builtin_amdgcn_s_setprio(0);
;         };
;     ...
;         if (grp == 1) H2((T - 1) & 1);
.LBB0_593:
	s_or_b64 exec, exec, s[58:59]
	s_and_saveexec_b64 s[50:51], s[44:45]
	s_cbranch_execz .LBB0_595
	v_add_u32_e32 v140, 0x9000, v205
	ds_read_b64 v[232:233], v140 offset:18432
	ds_read_b64 v[234:235], v140 offset:18464
	ds_read_b64 v[236:237], v140 offset:20736
	ds_read_b64 v[238:239], v140 offset:20768
	ds_read_b64 v[240:241], v140 offset:23040
	ds_read_b64 v[242:243], v140 offset:23072
	s_waitcnt lgkmcnt(4)
	v_mfma_f32_16x16x32_bf16 v[108:111], v[232:235], v[0:3], v[108:111]
	v_mfma_f32_16x16x32_bf16 v[80:83], v[232:235], v[8:11], v[80:83]
	ds_read_b64 v[232:233], v140 offset:25344
	ds_read_b64 v[234:235], v140 offset:25376
	v_sub_f32_e32 v120, v120, v248
	v_sub_f32_e32 v112, v112, v249
	v_exp_f32_e32 v120, v120
	v_exp_f32_e32 v112, v112
	v_sub_f32_e32 v121, v121, v248
	v_sub_f32_e32 v113, v113, v249
	v_exp_f32_e32 v121, v121
	v_exp_f32_e32 v113, v113
	s_waitcnt lgkmcnt(4)
	v_mfma_f32_16x16x32_bf16 v[104:107], v[236:239], v[0:3], v[104:107]
	v_mfma_f32_16x16x32_bf16 v[68:71], v[236:239], v[8:11], v[68:71]
	ds_read_b64 v[236:237], v140 offset:27648
	ds_read_b64 v[238:239], v140 offset:27680
	v_sub_f32_e32 v122, v122, v248
	v_sub_f32_e32 v114, v114, v249
	v_exp_f32_e32 v122, v122
	v_exp_f32_e32 v114, v114
	v_sub_f32_e32 v123, v123, v248
	v_sub_f32_e32 v115, v115, v249
	v_exp_f32_e32 v123, v123
	v_exp_f32_e32 v115, v115
	s_waitcnt lgkmcnt(4)
	v_mfma_f32_16x16x32_bf16 v[100:103], v[240:243], v[0:3], v[100:103]
	v_mfma_f32_16x16x32_bf16 v[60:63], v[240:243], v[8:11], v[60:63]
	ds_read_b64 v[240:241], v140 offset:29952
	ds_read_b64 v[242:243], v140 offset:29984
	v_sub_f32_e32 v124, v124, v248
	v_sub_f32_e32 v116, v116, v249
	v_exp_f32_e32 v124, v124
	v_exp_f32_e32 v116, v116
	v_sub_f32_e32 v125, v125, v248
	v_sub_f32_e32 v117, v117, v249
	v_exp_f32_e32 v125, v125
	v_exp_f32_e32 v117, v117
	s_waitcnt lgkmcnt(4)
	v_mfma_f32_16x16x32_bf16 v[96:99], v[232:235], v[0:3], v[96:99]
	v_mfma_f32_16x16x32_bf16 v[52:55], v[232:235], v[8:11], v[52:55]
	ds_read_b64 v[232:233], v140 offset:32256
	ds_read_b64 v[234:235], v140 offset:32288
	v_sub_f32_e32 v126, v126, v248
	v_sub_f32_e32 v118, v118, v249
	v_exp_f32_e32 v126, v126
	v_exp_f32_e32 v118, v118
	v_sub_f32_e32 v127, v127, v248
	v_sub_f32_e32 v119, v119, v249
	v_exp_f32_e32 v127, v127
	v_exp_f32_e32 v119, v119
	s_waitcnt lgkmcnt(4)
	v_mfma_f32_16x16x32_bf16 v[92:95], v[236:239], v[0:3], v[92:95]
	v_mfma_f32_16x16x32_bf16 v[44:47], v[236:239], v[8:11], v[44:47]
	ds_read_b64 v[236:237], v140 offset:34560
	ds_read_b64 v[238:239], v140 offset:34592
	v_add_f32_e32 v245, v120, v245
	v_add_f32_e32 v247, v112, v247
	v_add_f32_e32 v245, v121, v245
	v_add_f32_e32 v247, v113, v247
	v_add_f32_e32 v245, v122, v245
	v_add_f32_e32 v247, v114, v247
	v_add_f32_e32 v245, v123, v245
	v_add_f32_e32 v247, v115, v247
	s_waitcnt lgkmcnt(4)
	v_mfma_f32_16x16x32_bf16 v[84:87], v[240:243], v[0:3], v[84:87]
	v_mfma_f32_16x16x32_bf16 v[40:43], v[240:243], v[8:11], v[40:43]
	ds_read_b64 v[240:241], v140 offset:18496
	ds_read_b64 v[242:243], v140 offset:18528
	v_add_f32_e32 v245, v124, v245
	v_add_f32_e32 v247, v116, v247
	v_add_f32_e32 v245, v125, v245
	v_add_f32_e32 v247, v117, v247
	v_add_f32_e32 v245, v126, v245
	v_add_f32_e32 v247, v118, v247
	v_add_f32_e32 v245, v127, v245
	v_add_f32_e32 v247, v119, v247
	s_waitcnt lgkmcnt(4)
	v_mfma_f32_16x16x32_bf16 v[76:79], v[232:235], v[0:3], v[76:79]
	v_mfma_f32_16x16x32_bf16 v[36:39], v[232:235], v[8:11], v[36:39]
	ds_read_b64 v[232:233], v140 offset:20800
	ds_read_b64 v[234:235], v140 offset:20832
	v_cvt_pk_bf16_f32 v4, v120, v121
	v_cvt_pk_bf16_f32 v12, v112, v113
	v_cvt_pk_bf16_f32 v5, v122, v123
	v_cvt_pk_bf16_f32 v13, v114, v115
	v_cvt_pk_bf16_f32 v6, v124, v125
	v_cvt_pk_bf16_f32 v14, v116, v117
	v_cvt_pk_bf16_f32 v7, v126, v127
	v_cvt_pk_bf16_f32 v15, v118, v119
	s_waitcnt lgkmcnt(4)
	v_mfma_f32_16x16x32_bf16 v[64:67], v[236:239], v[0:3], v[64:67]
	v_mfma_f32_16x16x32_bf16 v[32:35], v[236:239], v[8:11], v[32:35]
	ds_read_b64 v[236:237], v140 offset:23104
	ds_read_b64 v[238:239], v140 offset:23136
	v_fma_f32 v250, v250, v244, v245
	v_fma_f32 v251, v251, v246, v247
	v_mov_b32_e32 v161, v250
	v_mov_b32_e32 v157, v251
	s_waitcnt lgkmcnt(4)
	v_mfma_f32_16x16x32_bf16 v[108:111], v[240:243], v[4:7], v[108:111]
	v_mfma_f32_16x16x32_bf16 v[80:83], v[240:243], v[12:15], v[80:83]
	ds_read_b64 v[240:241], v140 offset:25408
	ds_read_b64 v[242:243], v140 offset:25440
	s_waitcnt lgkmcnt(4)
	v_mfma_f32_16x16x32_bf16 v[104:107], v[232:235], v[4:7], v[104:107]
	v_mfma_f32_16x16x32_bf16 v[68:71], v[232:235], v[12:15], v[68:71]
	ds_read_b64 v[232:233], v140 offset:27712
	ds_read_b64 v[234:235], v140 offset:27744
	s_waitcnt lgkmcnt(4)
	v_mfma_f32_16x16x32_bf16 v[100:103], v[236:239], v[4:7], v[100:103]
	v_mfma_f32_16x16x32_bf16 v[60:63], v[236:239], v[12:15], v[60:63]
	ds_read_b64 v[236:237], v140 offset:30016
	ds_read_b64 v[238:239], v140 offset:30048
	s_waitcnt lgkmcnt(4)
	v_mfma_f32_16x16x32_bf16 v[96:99], v[240:243], v[4:7], v[96:99]
	v_mfma_f32_16x16x32_bf16 v[52:55], v[240:243], v[12:15], v[52:55]
	ds_read_b64 v[240:241], v140 offset:32320
	ds_read_b64 v[242:243], v140 offset:32352
	s_waitcnt lgkmcnt(4)
	v_mfma_f32_16x16x32_bf16 v[92:95], v[232:235], v[4:7], v[92:95]
	v_mfma_f32_16x16x32_bf16 v[44:47], v[232:235], v[12:15], v[44:47]
	ds_read_b64 v[232:233], v140 offset:34624
	ds_read_b64 v[234:235], v140 offset:34656
	s_waitcnt lgkmcnt(4)
	v_mfma_f32_16x16x32_bf16 v[84:87], v[236:239], v[4:7], v[84:87]
	v_mfma_f32_16x16x32_bf16 v[40:43], v[236:239], v[12:15], v[40:43]
	s_waitcnt lgkmcnt(2)
	v_mfma_f32_16x16x32_bf16 v[76:79], v[240:243], v[4:7], v[76:79]
	v_mfma_f32_16x16x32_bf16 v[36:39], v[240:243], v[12:15], v[36:39]
	s_waitcnt lgkmcnt(0)
	v_mfma_f32_16x16x32_bf16 v[64:67], v[232:235], v[4:7], v[64:67]
	v_mfma_f32_16x16x32_bf16 v[32:35], v[232:235], v[12:15], v[32:35]
